# adds: diff-attention K/V loop unrolled by two with exchanged register roles (drops 8 v_mov_b64 per tile)
# speedup vs baseline: 1.0335x; 1.0017x over previous
.LBB0_366:
	s_min_u32 s26, s24, 28
	s_mul_i32 s26, s26, 0x48000
	s_add_i32 s27, s17, s23
	s_add_i32 s58, s26, 0xd8000
	s_waitcnt vmcnt(4)
	s_barrier
	s_add_i32 s26, s22, 0
	v_add_u32_e32 v118, s26, v197
	v_add_u32_e32 v122, s26, v198
	v_add_u32_e32 v126, s26, v199
	ds_read_b128 v[114:117], v118 offset:0
	ds_read_b128 v[182:185], v118 offset:4096
	ds_read_b128 v[118:121], v122 offset:0
	ds_read_b128 v[178:181], v122 offset:4096
	ds_read_b128 v[122:125], v126 offset:0
	ds_read_b128 v[166:169], v126 offset:4096
	v_add_u32_e32 v150, s26, v200
	ds_read_b128 v[126:129], v150 offset:0
	ds_read_b128 v[146:149], v150 offset:4096
	s_add_i32 s25, s25, 0
	v_add_u32_e32 v210, s25, v201
	ds_read_b64_tr_b16 v[162:163], v210 offset:0
	ds_read_b64_tr_b16 v[164:165], v210 offset:2048
	v_add_u32_e32 v211, s25, v206
	ds_read_b64_tr_b16 v[158:159], v211 offset:0
	ds_read_b64_tr_b16 v[160:161], v211 offset:2048
	v_add_u32_e32 v223, s25, v207
	ds_read_b64_tr_b16 v[154:155], v223 offset:0
	ds_read_b64_tr_b16 v[156:157], v223 offset:2048
	v_add_u32_e32 v224, s25, v208
	ds_read_b64_tr_b16 v[150:151], v224 offset:0
	ds_read_b64_tr_b16 v[152:153], v224 offset:2048
	s_waitcnt lgkmcnt(0)
	s_setprio 1
	v_exp_f32_e32 v202, v82
	v_exp_f32_e32 v203, v83
	s_nop 0
	v_cvt_pk_bf16_f32 v170, v202, v203
	v_exp_f32_e32 v204, v84
	v_exp_f32_e32 v205, v85
	s_nop 0
	v_cvt_pk_bf16_f32 v171, v204, v205
	v_exp_f32_e32 v212, v86
	v_exp_f32_e32 v213, v87
	s_nop 0
	v_cvt_pk_bf16_f32 v172, v212, v213
	v_exp_f32_e32 v216, v88
	v_exp_f32_e32 v217, v89
	s_nop 0
	v_cvt_pk_bf16_f32 v173, v216, v217
	v_exp_f32_e32 v218, v90
	v_exp_f32_e32 v219, v91
	v_exp_f32_e32 v226, v92
	v_exp_f32_e32 v227, v93
	v_exp_f32_e32 v228, v94
	v_exp_f32_e32 v229, v95
	v_exp_f32_e32 v230, v96
	v_exp_f32_e32 v225, v97
	v_mfma_f32_32x32x16_bf16 v[82:97], v[114:117], v[130:133], v[2:17]
	v_add_f32_e32 v114, 0, v202
	v_add_f32_e32 v114, v203, v114
	v_add_f32_e32 v114, v204, v114
	v_add_f32_e32 v114, v205, v114
	v_add_f32_e32 v114, v212, v114
	v_add_f32_e32 v114, v213, v114
	v_add_f32_e32 v114, v216, v114
	v_mfma_f32_32x32x16_bf16 v[82:97], v[118:121], v[134:137], v[82:97]
	v_add_f32_e32 v114, v217, v114
	v_add_f32_e32 v114, v218, v114
	v_add_f32_e32 v114, v219, v114
	v_add_f32_e32 v114, v226, v114
	v_add_f32_e32 v114, v227, v114
	v_add_f32_e32 v114, v228, v114
	v_add_f32_e32 v114, v229, v114
	v_mfma_f32_32x32x16_bf16 v[82:97], v[122:125], v[138:141], v[82:97]
	v_add_f32_e32 v202, v230, v114
	v_mfma_f32_32x32x16_bf16 v[82:97], v[126:129], v[142:145], v[82:97]
	v_cvt_pk_bf16_f32 v177, v230, v225
	v_cvt_pk_bf16_f32 v174, v218, v219
	v_cvt_pk_bf16_f32 v175, v226, v227
	v_cvt_pk_bf16_f32 v176, v228, v229
	v_mfma_f32_32x32x16_bf16 v[114:129], v[182:185], v[130:133], v[2:17]
	v_mfma_f32_32x32x16_bf16 v[114:129], v[178:181], v[134:137], v[114:129]
	v_mfma_f32_32x32x16_bf16 v[114:129], v[166:169], v[138:141], v[114:129]
	s_setprio 0
	ds_read_b64_tr_b16 v[166:167], v210 offset:4096
	ds_read_b64_tr_b16 v[168:169], v210 offset:6144
	ds_read_b64_tr_b16 v[178:179], v211 offset:4096
	ds_read_b64_tr_b16 v[180:181], v211 offset:6144
	ds_read_b64_tr_b16 v[182:183], v223 offset:4096
	ds_read_b64_tr_b16 v[184:185], v223 offset:6144
	ds_read_b64_tr_b16 v[226:227], v224 offset:4096
	ds_read_b64_tr_b16 v[228:229], v224 offset:6144
	ds_read_b64_tr_b16 v[230:231], v210 offset:8192
	ds_read_b64_tr_b16 v[232:233], v210 offset:10240
	ds_read_b64_tr_b16 v[234:235], v211 offset:8192
	ds_read_b64_tr_b16 v[236:237], v211 offset:10240
	ds_read_b64_tr_b16 v[238:239], v223 offset:8192
	ds_read_b64_tr_b16 v[240:241], v223 offset:10240
	ds_read_b64_tr_b16 v[242:243], v224 offset:8192
	ds_read_b64_tr_b16 v[244:245], v224 offset:10240
	ds_read_b64_tr_b16 v[246:247], v210 offset:12288
	ds_read_b64_tr_b16 v[248:249], v210 offset:14336
	v_add_f32_e32 v225, v225, v202
	ds_read_b64_tr_b16 v[202:203], v211 offset:12288
	ds_read_b64_tr_b16 v[204:205], v211 offset:14336
	ds_read_b64_tr_b16 v[210:211], v223 offset:12288
	ds_read_b64_tr_b16 v[212:213], v223 offset:14336
	ds_read_b64_tr_b16 v[216:217], v224 offset:12288
	ds_read_b64_tr_b16 v[218:219], v224 offset:14336
	s_waitcnt lgkmcnt(15)
	s_setprio 1
	v_mfma_f32_32x32x16_bf16 v[66:81], v[162:165], v[170:173], v[66:81]
	v_exp_f32_e32 v162, v98
	v_exp_f32_e32 v163, v99
	s_nop 0
	v_cvt_pk_bf16_f32 v98, v162, v163
	v_mfma_f32_32x32x16_bf16 v[50:65], v[158:161], v[170:173], v[50:65]
	v_exp_f32_e32 v158, v100
	v_exp_f32_e32 v159, v101
	s_nop 0
	v_cvt_pk_bf16_f32 v99, v158, v159
	v_mfma_f32_32x32x16_bf16 v[34:49], v[154:157], v[170:173], v[34:49]
	v_exp_f32_e32 v154, v102
	v_exp_f32_e32 v155, v103
	s_nop 0
	v_cvt_pk_bf16_f32 v100, v154, v155
	v_mfma_f32_32x32x16_bf16 v[18:33], v[150:153], v[170:173], v[18:33]
	v_exp_f32_e32 v150, v104
	v_exp_f32_e32 v151, v105
	v_add_f32_e32 v152, v162, v225
	v_add_f32_e32 v152, v163, v152
	v_add_f32_e32 v152, v158, v152
	v_cvt_pk_bf16_f32 v101, v150, v151
	v_add_f32_e32 v152, v159, v152
	v_mfma_f32_32x32x16_bf16 v[66:81], v[166:169], v[174:177], v[66:81]
	v_exp_f32_e32 v106, v106
	v_exp_f32_e32 v107, v107
	v_add_f32_e32 v152, v154, v152
	v_add_f32_e32 v152, v155, v152
	v_add_f32_e32 v150, v150, v152
	v_cvt_pk_bf16_f32 v102, v106, v107
	v_add_f32_e32 v150, v151, v150
	v_mfma_f32_32x32x16_bf16 v[50:65], v[178:181], v[174:177], v[50:65]
	v_exp_f32_e32 v108, v108
	v_exp_f32_e32 v109, v109
	v_add_f32_e32 v106, v106, v150
	v_add_f32_e32 v106, v107, v106
	v_add_f32_e32 v106, v108, v106
	v_cvt_pk_bf16_f32 v103, v108, v109
	v_add_f32_e32 v106, v109, v106
	v_mfma_f32_32x32x16_bf16 v[34:49], v[182:185], v[174:177], v[34:49]
	v_exp_f32_e32 v110, v110
	v_exp_f32_e32 v111, v111
	v_add_f32_e32 v106, v110, v106
	v_cvt_pk_bf16_f32 v104, v110, v111
	v_add_f32_e32 v106, v111, v106
	v_mfma_f32_32x32x16_bf16 v[18:33], v[226:229], v[174:177], v[18:33]
	v_exp_f32_e32 v112, v112
	v_exp_f32_e32 v113, v113
	v_add_f32_e32 v106, v112, v106
	v_cvt_pk_bf16_f32 v105, v112, v113
	v_add_f32_e32 v106, v113, v106
	v_mfma_f32_32x32x16_bf16 v[114:129], v[146:149], v[142:145], v[114:129]
	s_waitcnt lgkmcnt(0)
	v_mfma_f32_32x32x16_bf16 v[66:81], v[230:233], v[98:101], v[66:81]
	v_add_f32_e32 v209, v209, v106
	v_mfma_f32_32x32x16_bf16 v[50:65], v[234:237], v[98:101], v[50:65]
	v_lshl_add_u64 v[108:109], v[186:187], 0, s[58:59]
	s_mov_b32 m0, s27
	s_nop 0
	global_load_lds_dwordx4 v[108:109], off
	v_mfma_f32_32x32x16_bf16 v[34:49], v[238:241], v[98:101], v[34:49]
	v_mfma_f32_32x32x16_bf16 v[18:33], v[242:245], v[98:101], v[18:33]
	v_lshl_add_u64 v[108:109], v[108:109], 0, s[28:29]
	s_add_i32 m0, s27, 0x2000
	s_nop 0
	global_load_lds_dwordx4 v[108:109], off
	v_mfma_f32_32x32x16_bf16 v[66:81], v[246:249], v[102:105], v[66:81]
	v_mfma_f32_32x32x16_bf16 v[50:65], v[202:205], v[102:105], v[50:65]
	v_lshl_add_u64 v[108:109], v[188:189], 0, s[58:59]
	s_add_i32 m0, s27, 0x4000
	s_nop 0
	global_load_lds_dwordx4 v[108:109], off
	v_mfma_f32_32x32x16_bf16 v[34:49], v[210:213], v[102:105], v[34:49]
	v_mfma_f32_32x32x16_bf16 v[18:33], v[216:219], v[102:105], v[18:33]
	v_lshl_add_u64 v[108:109], v[108:109], 0, s[34:35]
	s_add_i32 m0, s27, 0x6000
	s_nop 0
	global_load_lds_dwordx4 v[108:109], off
	s_setprio 0
	s_add_i32 s26, s22, 0x8000
	s_cmp_lg_u32 s22, 0x18000
	s_mov_b32 s25, s22
	s_cselect_b32 s22, s26, 0
	s_add_i32 s26, s23, 0x8000
	s_cmp_lg_u32 s23, 0x18000
	s_cselect_b32 s23, s26, 0
	s_add_i32 s24, s24, 1
	s_min_u32 s26, s24, 28
	s_mul_i32 s26, s26, 0x48000
	s_add_i32 s27, s17, s23
	s_add_i32 s58, s26, 0xd8000
	s_waitcnt vmcnt(4)
	s_barrier
	s_add_i32 s26, s22, 0
	v_add_u32_e32 v102, s26, v197
	v_add_u32_e32 v106, s26, v198
	v_add_u32_e32 v110, s26, v199
	ds_read_b128 v[98:101], v102 offset:0
	ds_read_b128 v[182:185], v102 offset:4096
	ds_read_b128 v[102:105], v106 offset:0
	ds_read_b128 v[178:181], v106 offset:4096
	ds_read_b128 v[106:109], v110 offset:0
	ds_read_b128 v[166:169], v110 offset:4096
	v_add_u32_e32 v150, s26, v200
	ds_read_b128 v[110:113], v150 offset:0
	ds_read_b128 v[146:149], v150 offset:4096
	s_add_i32 s25, s25, 0
	v_add_u32_e32 v210, s25, v201
	ds_read_b64_tr_b16 v[162:163], v210 offset:0
	ds_read_b64_tr_b16 v[164:165], v210 offset:2048
	v_add_u32_e32 v211, s25, v206
	ds_read_b64_tr_b16 v[158:159], v211 offset:0
	ds_read_b64_tr_b16 v[160:161], v211 offset:2048
	v_add_u32_e32 v223, s25, v207
	ds_read_b64_tr_b16 v[154:155], v223 offset:0
	ds_read_b64_tr_b16 v[156:157], v223 offset:2048
	v_add_u32_e32 v224, s25, v208
	ds_read_b64_tr_b16 v[150:151], v224 offset:0
	ds_read_b64_tr_b16 v[152:153], v224 offset:2048
	s_waitcnt lgkmcnt(0)
	s_setprio 1
	v_exp_f32_e32 v202, v82
	v_exp_f32_e32 v203, v83
	s_nop 0
	v_cvt_pk_bf16_f32 v170, v202, v203
	v_exp_f32_e32 v204, v84
	v_exp_f32_e32 v205, v85
	s_nop 0
	v_cvt_pk_bf16_f32 v171, v204, v205
	v_exp_f32_e32 v212, v86
	v_exp_f32_e32 v213, v87
	s_nop 0
	v_cvt_pk_bf16_f32 v172, v212, v213
	v_exp_f32_e32 v216, v88
	v_exp_f32_e32 v217, v89
	s_nop 0
	v_cvt_pk_bf16_f32 v173, v216, v217
	v_exp_f32_e32 v218, v90
	v_exp_f32_e32 v219, v91
	v_exp_f32_e32 v226, v92
	v_exp_f32_e32 v227, v93
	v_exp_f32_e32 v228, v94
	v_exp_f32_e32 v229, v95
	v_exp_f32_e32 v230, v96
	v_exp_f32_e32 v225, v97
	v_mfma_f32_32x32x16_bf16 v[82:97], v[98:101], v[130:133], v[2:17]
	v_add_f32_e32 v98, 0, v202
	v_add_f32_e32 v98, v203, v98
	v_add_f32_e32 v98, v204, v98
	v_add_f32_e32 v98, v205, v98
	v_add_f32_e32 v98, v212, v98
	v_add_f32_e32 v98, v213, v98
	v_add_f32_e32 v98, v216, v98
	v_mfma_f32_32x32x16_bf16 v[82:97], v[102:105], v[134:137], v[82:97]
	v_add_f32_e32 v98, v217, v98
	v_add_f32_e32 v98, v218, v98
	v_add_f32_e32 v98, v219, v98
	v_add_f32_e32 v98, v226, v98
	v_add_f32_e32 v98, v227, v98
	v_add_f32_e32 v98, v228, v98
	v_add_f32_e32 v98, v229, v98
	v_mfma_f32_32x32x16_bf16 v[82:97], v[106:109], v[138:141], v[82:97]
	v_add_f32_e32 v202, v230, v98
	v_mfma_f32_32x32x16_bf16 v[82:97], v[110:113], v[142:145], v[82:97]
	v_cvt_pk_bf16_f32 v177, v230, v225
	v_cvt_pk_bf16_f32 v174, v218, v219
	v_cvt_pk_bf16_f32 v175, v226, v227
	v_cvt_pk_bf16_f32 v176, v228, v229
	v_mfma_f32_32x32x16_bf16 v[98:113], v[182:185], v[130:133], v[2:17]
	v_mfma_f32_32x32x16_bf16 v[98:113], v[178:181], v[134:137], v[98:113]
	v_mfma_f32_32x32x16_bf16 v[98:113], v[166:169], v[138:141], v[98:113]
	s_setprio 0
	ds_read_b64_tr_b16 v[166:167], v210 offset:4096
	ds_read_b64_tr_b16 v[168:169], v210 offset:6144
	ds_read_b64_tr_b16 v[178:179], v211 offset:4096
	ds_read_b64_tr_b16 v[180:181], v211 offset:6144
	ds_read_b64_tr_b16 v[182:183], v223 offset:4096
	ds_read_b64_tr_b16 v[184:185], v223 offset:6144
	ds_read_b64_tr_b16 v[226:227], v224 offset:4096
	ds_read_b64_tr_b16 v[228:229], v224 offset:6144
	ds_read_b64_tr_b16 v[230:231], v210 offset:8192
	ds_read_b64_tr_b16 v[232:233], v210 offset:10240
	ds_read_b64_tr_b16 v[234:235], v211 offset:8192
	ds_read_b64_tr_b16 v[236:237], v211 offset:10240
	ds_read_b64_tr_b16 v[238:239], v223 offset:8192
	ds_read_b64_tr_b16 v[240:241], v223 offset:10240
	ds_read_b64_tr_b16 v[242:243], v224 offset:8192
	ds_read_b64_tr_b16 v[244:245], v224 offset:10240
	ds_read_b64_tr_b16 v[246:247], v210 offset:12288
	ds_read_b64_tr_b16 v[248:249], v210 offset:14336
	v_add_f32_e32 v225, v225, v202
	ds_read_b64_tr_b16 v[202:203], v211 offset:12288
	ds_read_b64_tr_b16 v[204:205], v211 offset:14336
	ds_read_b64_tr_b16 v[210:211], v223 offset:12288
	ds_read_b64_tr_b16 v[212:213], v223 offset:14336
	ds_read_b64_tr_b16 v[216:217], v224 offset:12288
	ds_read_b64_tr_b16 v[218:219], v224 offset:14336
	s_waitcnt lgkmcnt(15)
	s_setprio 1
	v_mfma_f32_32x32x16_bf16 v[66:81], v[162:165], v[170:173], v[66:81]
	v_exp_f32_e32 v162, v114
	v_exp_f32_e32 v163, v115
	s_nop 0
	v_cvt_pk_bf16_f32 v114, v162, v163
	v_mfma_f32_32x32x16_bf16 v[50:65], v[158:161], v[170:173], v[50:65]
	v_exp_f32_e32 v158, v116
	v_exp_f32_e32 v159, v117
	s_nop 0
	v_cvt_pk_bf16_f32 v115, v158, v159
	v_mfma_f32_32x32x16_bf16 v[34:49], v[154:157], v[170:173], v[34:49]
	v_exp_f32_e32 v154, v118
	v_exp_f32_e32 v155, v119
	s_nop 0
	v_cvt_pk_bf16_f32 v116, v154, v155
	v_mfma_f32_32x32x16_bf16 v[18:33], v[150:153], v[170:173], v[18:33]
	v_exp_f32_e32 v150, v120
	v_exp_f32_e32 v151, v121
	v_add_f32_e32 v152, v162, v225
	v_add_f32_e32 v152, v163, v152
	v_add_f32_e32 v152, v158, v152
	v_cvt_pk_bf16_f32 v117, v150, v151
	v_add_f32_e32 v152, v159, v152
	v_mfma_f32_32x32x16_bf16 v[66:81], v[166:169], v[174:177], v[66:81]
	v_exp_f32_e32 v122, v122
	v_exp_f32_e32 v123, v123
	v_add_f32_e32 v152, v154, v152
	v_add_f32_e32 v152, v155, v152
	v_add_f32_e32 v150, v150, v152
	v_cvt_pk_bf16_f32 v118, v122, v123
	v_add_f32_e32 v150, v151, v150
	v_mfma_f32_32x32x16_bf16 v[50:65], v[178:181], v[174:177], v[50:65]
	v_exp_f32_e32 v124, v124
	v_exp_f32_e32 v125, v125
	v_add_f32_e32 v122, v122, v150
	v_add_f32_e32 v122, v123, v122
	v_add_f32_e32 v122, v124, v122
	v_cvt_pk_bf16_f32 v119, v124, v125
	v_add_f32_e32 v122, v125, v122
	v_mfma_f32_32x32x16_bf16 v[34:49], v[182:185], v[174:177], v[34:49]
	v_exp_f32_e32 v126, v126
	v_exp_f32_e32 v127, v127
	v_add_f32_e32 v122, v126, v122
	v_cvt_pk_bf16_f32 v120, v126, v127
	v_add_f32_e32 v122, v127, v122
	v_mfma_f32_32x32x16_bf16 v[18:33], v[226:229], v[174:177], v[18:33]
	v_exp_f32_e32 v128, v128
	v_exp_f32_e32 v129, v129
	v_add_f32_e32 v122, v128, v122
	v_cvt_pk_bf16_f32 v121, v128, v129
	v_add_f32_e32 v122, v129, v122
	v_mfma_f32_32x32x16_bf16 v[98:113], v[146:149], v[142:145], v[98:113]
	s_waitcnt lgkmcnt(0)
	v_mfma_f32_32x32x16_bf16 v[66:81], v[230:233], v[114:117], v[66:81]
	v_add_f32_e32 v209, v209, v122
	v_mfma_f32_32x32x16_bf16 v[50:65], v[234:237], v[114:117], v[50:65]
	v_lshl_add_u64 v[124:125], v[186:187], 0, s[58:59]
	s_mov_b32 m0, s27
	s_nop 0
	global_load_lds_dwordx4 v[124:125], off
	v_mfma_f32_32x32x16_bf16 v[34:49], v[238:241], v[114:117], v[34:49]
	v_mfma_f32_32x32x16_bf16 v[18:33], v[242:245], v[114:117], v[18:33]
	v_lshl_add_u64 v[124:125], v[124:125], 0, s[28:29]
	s_add_i32 m0, s27, 0x2000
	s_nop 0
	global_load_lds_dwordx4 v[124:125], off
	v_mfma_f32_32x32x16_bf16 v[66:81], v[246:249], v[118:121], v[66:81]
	v_mfma_f32_32x32x16_bf16 v[50:65], v[202:205], v[118:121], v[50:65]
	v_lshl_add_u64 v[124:125], v[188:189], 0, s[58:59]
	s_add_i32 m0, s27, 0x4000
	s_nop 0
	global_load_lds_dwordx4 v[124:125], off
	v_mfma_f32_32x32x16_bf16 v[34:49], v[210:213], v[118:121], v[34:49]
	v_mfma_f32_32x32x16_bf16 v[18:33], v[216:219], v[118:121], v[18:33]
	v_lshl_add_u64 v[124:125], v[124:125], 0, s[34:35]
	s_add_i32 m0, s27, 0x6000
	s_nop 0
	global_load_lds_dwordx4 v[124:125], off
	s_setprio 0
	s_add_i32 s26, s22, 0x8000
	s_cmp_lg_u32 s22, 0x18000
	s_mov_b32 s25, s22
	s_cselect_b32 s22, s26, 0
	s_add_i32 s26, s23, 0x8000
	s_cmp_lg_u32 s23, 0x18000
	s_cselect_b32 s23, s26, 0
	s_add_i32 s24, s24, 1
	s_cmp_eq_u32 s24, 32
	s_cbranch_scc0 .LBB0_366
	global_load_dwordx4 v[98:101], v0, s[10:11]
	global_load_dwordx4 v[102:105], v0, s[10:11] offset:32
	global_load_dwordx4 v[106:109], v0, s[10:11] offset:64
	global_load_dwordx4 v[110:113], v0, s[10:11] offset:96
	global_load_dwordx4 v[114:117], v0, s[10:11] offset:128
	global_load_dwordx4 v[118:121], v0, s[10:11] offset:160
	global_load_dwordx4 v[122:125], v0, s[10:11] offset:192
	global_load_dwordx4 v[126:129], v0, s[10:11] offset:224
	global_load_dwordx4 v[130:133], v0, s[10:11] offset:256
	global_load_dwordx4 v[134:137], v0, s[10:11] offset:288
	global_load_dwordx4 v[138:141], v0, s[10:11] offset:320
	global_load_dwordx4 v[142:145], v0, s[10:11] offset:352
	global_load_dwordx4 v[146:149], v0, s[10:11] offset:384
	global_load_dwordx4 v[150:153], v0, s[10:11] offset:416
	global_load_dwordx4 v[154:157], v0, s[10:11] offset:448
	global_load_dwordx4 v[158:161], v0, s[10:11] offset:480
	ds_bpermute_b32 v82, v221, v209
	s_lshl_b32 s17, s21, 14
	s_add_i32 s17, s17, 0
	s_waitcnt vmcnt(0)
	s_cmp_eq_u32 s16, 0
	s_waitcnt lgkmcnt(0)
	v_add_f32_e32 v82, v209, v82
	v_div_scale_f32 v83, s[22:23], v82, v82, 1.0
	v_rcp_f32_e32 v84, v83
	v_div_scale_f32 v85, vcc, 1.0, v82, 1.0
	v_lshl_add_u32 v92, v196, 4, s17
	v_fma_f32 v86, -v83, v84, 1.0
	v_fmac_f32_e32 v84, v86, v84
	v_mul_f32_e32 v86, v85, v84
	v_fma_f32 v87, -v83, v86, v85
	v_fmac_f32_e32 v86, v87, v84
	v_fma_f32 v83, -v83, v86, v85
	v_div_fmas_f32 v83, v83, v84, v86
	s_cselect_b64 s[16:17], -1, 0
	v_div_fixup_f32 v82, v83, v82, 1.0
	s_and_b64 vcc, exec, s[16:17]
	s_waitcnt vmcnt(0)
	s_barrier
	s_cbranch_vccnz .LBB0_369
	v_pk_mul_f32 v[86:87], v[68:69], v[82:83] op_sel_hi:[1,0]
	v_pk_mul_f32 v[84:85], v[66:67], v[82:83] op_sel_hi:[1,0]
	ds_write_b128 v92, v[84:87]
	v_pk_mul_f32 v[86:87], v[72:73], v[82:83] op_sel_hi:[1,0]
	v_pk_mul_f32 v[84:85], v[70:71], v[82:83] op_sel_hi:[1,0]
	ds_write_b128 v92, v[84:87] offset:1024
	v_pk_mul_f32 v[86:87], v[76:77], v[82:83] op_sel_hi:[1,0]
	v_pk_mul_f32 v[84:85], v[74:75], v[82:83] op_sel_hi:[1,0]
	ds_write_b128 v92, v[84:87] offset:2048
	v_pk_mul_f32 v[86:87], v[80:81], v[82:83] op_sel_hi:[1,0]
	v_pk_mul_f32 v[84:85], v[78:79], v[82:83] op_sel_hi:[1,0]
	ds_write_b128 v92, v[84:87] offset:3072
	v_pk_mul_f32 v[86:87], v[52:53], v[82:83] op_sel_hi:[1,0]
	v_pk_mul_f32 v[84:85], v[50:51], v[82:83] op_sel_hi:[1,0]
	ds_write_b128 v92, v[84:87] offset:4096
	v_pk_mul_f32 v[86:87], v[56:57], v[82:83] op_sel_hi:[1,0]
	v_pk_mul_f32 v[84:85], v[54:55], v[82:83] op_sel_hi:[1,0]
	ds_write_b128 v92, v[84:87] offset:5120
	v_pk_mul_f32 v[86:87], v[60:61], v[82:83] op_sel_hi:[1,0]
	v_pk_mul_f32 v[84:85], v[58:59], v[82:83] op_sel_hi:[1,0]
	ds_write_b128 v92, v[84:87] offset:6144
	v_pk_mul_f32 v[86:87], v[64:65], v[82:83] op_sel_hi:[1,0]
	v_pk_mul_f32 v[84:85], v[62:63], v[82:83] op_sel_hi:[1,0]
	ds_write_b128 v92, v[84:87] offset:7168
	v_pk_mul_f32 v[86:87], v[36:37], v[82:83] op_sel_hi:[1,0]
	v_pk_mul_f32 v[84:85], v[34:35], v[82:83] op_sel_hi:[1,0]
	ds_write_b128 v92, v[84:87] offset:8192
	v_pk_mul_f32 v[86:87], v[40:41], v[82:83] op_sel_hi:[1,0]
	v_pk_mul_f32 v[84:85], v[38:39], v[82:83] op_sel_hi:[1,0]
	ds_write_b128 v92, v[84:87] offset:9216
	v_pk_mul_f32 v[86:87], v[44:45], v[82:83] op_sel_hi:[1,0]
	v_pk_mul_f32 v[84:85], v[42:43], v[82:83] op_sel_hi:[1,0]
	ds_write_b128 v92, v[84:87] offset:10240
	v_pk_mul_f32 v[86:87], v[48:49], v[82:83] op_sel_hi:[1,0]
	v_pk_mul_f32 v[84:85], v[46:47], v[82:83] op_sel_hi:[1,0]
	ds_write_b128 v92, v[84:87] offset:11264
	v_pk_mul_f32 v[86:87], v[20:21], v[82:83] op_sel_hi:[1,0]
	v_pk_mul_f32 v[84:85], v[18:19], v[82:83] op_sel_hi:[1,0]
	ds_write_b128 v92, v[84:87] offset:12288
	v_pk_mul_f32 v[86:87], v[24:25], v[82:83] op_sel_hi:[1,0]
	v_pk_mul_f32 v[84:85], v[22:23], v[82:83] op_sel_hi:[1,0]
	ds_write_b128 v92, v[84:87] offset:13312
	v_pk_mul_f32 v[86:87], v[28:29], v[82:83] op_sel_hi:[1,0]
	v_pk_mul_f32 v[84:85], v[26:27], v[82:83] op_sel_hi:[1,0]
	ds_write_b128 v92, v[84:87] offset:14336
	v_pk_mul_f32 v[86:87], v[32:33], v[82:83] op_sel_hi:[1,0]
	v_pk_mul_f32 v[84:85], v[30:31], v[82:83] op_sel_hi:[1,0]
	ds_write_b128 v92, v[84:87] offset:15360
